# GLA recurrence rewritten by hand: shared gv/q fragments staged once per CU through an LDS-DMA ring (4 slots), per-wave kdec/decay loads 2 chunks ahead; P7 GLA-norm loop prefetches next token
# speedup vs baseline: 1.0067x; 1.0067x over previous
; __device__ __forceinline__ void gla_item(LAS unsigned char* lds, int item, const bf16_t* KDT, const float* DEC, const bf16_t* GVT, const bf16_t* GQF, bf16_t* OG) {
;     const int tid = threadIdx.x, wid = __builtin_amdgcn_readfirstlane(tid >> 6), lane = tid & 63, fr = lane & 15, fq = lane >> 4;
;     const int vs = item & 7, h = (item >> 3) & 3, b = item >> 5;
;     const bf16_t* kdt = KDT + (size_t)((b * 4 + h) * 32) * 8192 + (size_t)(wid * 2 * 64 + lane) * 8;
;     const float* dec = DEC + (size_t)((b * 4 + h) * 32) * 128 + 16 * wid + 4 * fq;
;     const bf16_t* gvt = GVT + (size_t)item * (32 * 4 * 512) + (size_t)lane * 8;
;     const int f0 = 16 * (wid & 3), v0 = 16 * (wid >> 2);
;     const bf16_t* gq = GQF + ((size_t)((b * 4 + h) * 32) * 16 + (size_t)(wid & 3) * 4) * 512 + (size_t)lane * 8;
;     bf16_t* outp = OG + (size_t)item * (SEQ * 32) + (size_t)(f0 + fr) * 32 + v0 + 4 * fq;
;     f32x4 S[2]; S[0] = (f32x4){0.f, 0.f, 0.f, 0.f}; S[1] = S[0];
;     ...
;     GlaSet s0, s1, s2;
;     GLA_LOAD(s0, 0); GLA_LOAD(s1, 1);
; #pragma unroll 1
;     for (int c = 0; c < 30; c += 3) {
;         GLA_LOAD(s2, c + 2); GLA_STEP(s0, c);
;         GLA_LOAD(s0, c + 3); GLA_STEP(s1, c + 1);
;         GLA_LOAD(s1, c + 4); GLA_STEP(s2, c + 2);
;     }
.LBB0_982:
	v_readfirstlane_b32 s53, v185
	v_lshlrev_b32_e32 v0, 4, v184
	v_lshrrev_b32_e32 v6, 4, v184
	v_and_b32_e32 v7, 15, v184
	s_lshr_b32 s53, s53, 6
	v_lshlrev_b32_e32 v1, 4, v6
	s_and_b32 s0, s52, 7
	s_lshl_b32 s0, s0, 2
	s_lshr_b32 s55, s52, 6
	s_add_i32 s0, s0, s55
	s_bfe_u32 s55, s52, 0x30003
	s_lshl_b32 s69, s0, 3
	s_add_i32 s69, s69, s55
	s_lshl_b32 s36, s0, 19
	s_lshl_b32 s37, s53, 11
	s_add_i32 s36, s36, s37
	s_add_u32 s58, s86, 0x14000000
	s_addc_u32 s59, s87, 0
	s_add_u32 s58, s58, s36
	s_addc_u32 s59, s59, 0
	s_lshl_b32 s36, s0, 14
	s_lshl_b32 s37, s53, 6
	s_add_i32 s36, s36, s37
	s_add_u32 s60, s86, 0x15000000
	s_addc_u32 s61, s87, 0
	s_add_u32 s60, s60, s36
	s_addc_u32 s61, s61, 0
	s_lshl_b32 s36, s69, 17
	s_add_u32 s62, s86, 0x10800000
	s_addc_u32 s63, s87, 0
	s_add_u32 s62, s62, s36
	s_addc_u32 s63, s63, 0
	s_add_u32 s66, s86, 0x1e000000
	s_addc_u32 s67, s87, 0
	s_add_u32 s66, s66, s36
	s_addc_u32 s67, s67, 0
	s_and_b32 s36, s53, 3
	s_lshl_b32 s36, s36, 12
	s_lshr_b32 s37, s53, 2
	s_lshl_b32 s37, s37, 11
	s_add_i32 s55, s36, s37
	s_lshl_b32 s37, s0, 19
	s_add_u32 s64, s86, 0x6800000
	s_addc_u32 s65, s87, 0
	s_add_u32 s64, s64, s37
	s_addc_u32 s65, s65, 0
	s_add_u32 s64, s64, s55
	s_addc_u32 s65, s65, 0
	s_add_i32 s36, s36, 0x1000
	v_add_u32_e32 v108, s36, v0
	s_and_b32 s36, s53, 3
	s_lshl_b32 s36, s36, 4
	v_add_u32_e32 v2, s36, v7
	v_lshlrev_b32_e32 v2, 5, v2
	s_lshr_b32 s37, s53, 2
	s_lshl_b32 s37, s37, 4
	v_lshl_add_u32 v2, v6, 2, v2
	v_add_u32_e32 v2, s37, v2
	v_lshlrev_b32_e32 v2, 1, v2
	v_mul_u32_u24_e32 v3, 0x110, v7
	s_lshl_b32 s36, s53, 5
	v_lshl_add_u32 v3, v6, 3, v3
	v_add_u32_e32 v3, s36, v3
	v_add_u32_e32 v4, s37, v7
	v_mul_u32_u24_e32 v4, 0x110, v4
	v_lshl_add_u32 v4, v6, 4, v4
	s_lshr_b32 s36, s53, 1
	s_lshl_b32 s36, s36, 10
	v_add_u32_e32 v109, s36, v0
	s_and_b32 s37, s53, 1
	s_add_i32 s53, s55, 0x1000
	s_mov_b32 s55, s36
	s_cmp_lg_u32 s37, 0
	s_cselect_b32 s36, 0, -1
	s_cselect_b32 s37, -1, 0
	s_mov_b32 s0, 0x5000
	s_mov_b64 exec, s[36:37]
	s_add_i32 m0, s0, s55
	s_nop 0
	global_load_lds_dwordx4 v109, s[62:63]
	s_mov_b64 exec, -1
	s_add_i32 m0, s0, s53
	s_nop 0
	global_load_lds_dwordx4 v0, s[64:65]
	global_load_lds_dwordx4 v0, s[64:65] offset:1024
	s_add_u32 s62, s62, 0x1000
	s_addc_u32 s63, s63, 0
	s_add_u32 s64, s64, 0x4000
	s_addc_u32 s65, s65, 0
	s_mov_b32 s0, 0xa000
	s_mov_b64 exec, s[36:37]
	s_add_i32 m0, s0, s55
	s_nop 0
	global_load_lds_dwordx4 v109, s[62:63]
	s_mov_b64 exec, -1
	s_add_i32 m0, s0, s53
	s_nop 0
	global_load_lds_dwordx4 v0, s[64:65]
	global_load_lds_dwordx4 v0, s[64:65] offset:1024
	s_add_u32 s62, s62, 0x1000
	s_addc_u32 s63, s63, 0
	s_add_u32 s64, s64, 0x4000
	s_addc_u32 s65, s65, 0
	s_mov_b32 s0, 0xf000
	s_mov_b64 exec, s[36:37]
	s_add_i32 m0, s0, s55
	s_nop 0
	global_load_lds_dwordx4 v109, s[62:63]
	s_mov_b64 exec, -1
	s_add_i32 m0, s0, s53
	s_nop 0
	global_load_lds_dwordx4 v0, s[64:65]
	global_load_lds_dwordx4 v0, s[64:65] offset:1024
	s_add_u32 s62, s62, 0x1000
	s_addc_u32 s63, s63, 0
	s_add_u32 s64, s64, 0x4000
	s_addc_u32 s65, s65, 0
	global_load_dwordx4 v[16:19], v0, s[58:59]
	global_load_dwordx4 v[20:23], v0, s[58:59] offset:1024
	global_load_dwordx4 v[24:27], v1, s[60:61]
	s_add_u32 s58, s58, 0x4000
	s_addc_u32 s59, s59, 0
	s_add_u32 s60, s60, 0x200
	s_addc_u32 s61, s61, 0
	global_load_dwordx4 v[28:31], v0, s[58:59]
	global_load_dwordx4 v[32:35], v0, s[58:59] offset:1024
	global_load_dwordx4 v[36:39], v1, s[60:61]
	s_add_u32 s58, s58, 0x4000
	s_addc_u32 s59, s59, 0
	s_add_u32 s60, s60, 0x200
	s_addc_u32 s61, s61, 0
	v_mov_b32_e32 v8, 0
	v_mov_b32_e32 v9, 0
	v_mov_b32_e32 v10, 0
	v_mov_b32_e32 v11, 0
	v_mov_b32_e32 v12, 0
	v_mov_b32_e32 v13, 0
	v_mov_b32_e32 v14, 0
	v_mov_b32_e32 v15, 0
	s_mov_b32 s54, 0
	s_mov_b32 s68, 0x5000
	s_waitcnt vmcnt(0)
	s_barrier
.Lgla_loop:
	s_waitcnt vmcnt(11)
	v_add_u32_e32 v5, s68, v0
	ds_read_b128 v[52:55], v5
	ds_read_b128 v[56:59], v5 offset:1024
	ds_read_b128 v[60:63], v5 offset:2048
	ds_read_b128 v[64:67], v5 offset:3072
	v_pk_mul_f32 v[8:9], v[8:9], v[24:25]
	v_pk_mul_f32 v[10:11], v[10:11], v[26:27]
	v_pk_mul_f32 v[12:13], v[12:13], v[24:25]
	v_pk_mul_f32 v[14:15], v[14:15], v[26:27]
	s_and_b32 s69, s54, 1
	s_mulk_i32 s69, 0x2200
	v_add_u32_e32 v6, s69, v3
	v_add_u32_e32 v7, s69, v4
	s_waitcnt lgkmcnt(0)
	s_nop 0
	v_mfma_f32_16x16x32_bf16 v[8:11], v[16:19], v[52:55], v[8:11]
	v_mfma_f32_16x16x32_bf16 v[12:15], v[16:19], v[60:63], v[12:15]
	v_mfma_f32_16x16x32_bf16 v[8:11], v[20:23], v[56:59], v[8:11]
	v_mfma_f32_16x16x32_bf16 v[12:15], v[20:23], v[64:67], v[12:15]
	global_load_dwordx4 v[40:43], v0, s[58:59]
	global_load_dwordx4 v[44:47], v0, s[58:59] offset:1024
	global_load_dwordx4 v[48:51], v1, s[60:61]
	s_add_u32 s58, s58, 0x4000
	s_addc_u32 s59, s59, 0
	s_add_u32 s60, s60, 0x200
	s_addc_u32 s61, s61, 0
	s_nop 7
	v_cvt_pk_bf16_f32 v104, v8, v9
	v_cvt_pk_bf16_f32 v105, v10, v11
	v_cvt_pk_bf16_f32 v106, v12, v13
	v_cvt_pk_bf16_f32 v107, v14, v15
	ds_write_b64 v6, v[104:105]
	ds_write_b64 v6, v[106:107] offset:4352
	s_waitcnt vmcnt(11)
	s_waitcnt lgkmcnt(0)
	s_barrier
	v_add_u32_e32 v5, s68, v108
	ds_read_b128 v[68:71], v7
	ds_read_b128 v[72:75], v7 offset:64
	ds_read_b128 v[76:79], v7 offset:128
	ds_read_b128 v[80:83], v7 offset:192
	ds_read_b128 v[84:87], v5
	ds_read_b128 v[88:91], v5 offset:1024
	ds_read_b128 v[92:95], v5 offset:2048
	ds_read_b128 v[96:99], v5 offset:3072
	s_add_i32 s0, s68, 0xffffb000
	s_cmp_lg_u32 s68, 0x5000
	s_cselect_b32 s0, s0, 0x14000
	s_mov_b64 exec, s[36:37]
	s_add_i32 m0, s0, s55
	s_nop 0
	global_load_lds_dwordx4 v109, s[62:63]
	s_mov_b64 exec, -1
	s_add_i32 m0, s0, s53
	s_nop 0
	global_load_lds_dwordx4 v0, s[64:65]
	global_load_lds_dwordx4 v0, s[64:65] offset:1024
	s_add_u32 s62, s62, 0x1000
	s_addc_u32 s63, s63, 0
	s_add_u32 s64, s64, 0x4000
	s_addc_u32 s65, s65, 0
	s_waitcnt lgkmcnt(0)
	v_mfma_f32_16x16x32_bf16 v[100:103], v[68:71], v[84:87], 0
	v_mfma_f32_16x16x32_bf16 v[100:103], v[72:75], v[88:91], v[100:103]
	v_mfma_f32_16x16x32_bf16 v[100:103], v[76:79], v[92:95], v[100:103]
	v_mfma_f32_16x16x32_bf16 v[100:103], v[80:83], v[96:99], v[100:103]
	s_add_i32 s68, s68, 0x5000
	s_cmp_lg_u32 s68, 0x19000
	s_cselect_b32 s68, s68, 0x5000
	s_nop 7
	v_pk_mul_f32 v[100:101], v[100:101], s[22:23] op_sel_hi:[1,0]
	v_pk_mul_f32 v[102:103], v[102:103], s[22:23] op_sel_hi:[1,0]
	s_cmpk_lt_u32 s54, 0x20
	v_cvt_pk_bf16_f32 v104, v100, v101
	v_cvt_pk_bf16_f32 v105, v102, v103
	s_cbranch_scc0 .Lgla_nost0
	global_store_dwordx2 v2, v[104:105], s[66:67]
; __device__ __forceinline__ void gla_item(LAS unsigned char* lds, int item, const bf16_t* KDT, const float* DEC, const bf16_t* GVT, const bf16_t* GQF, bf16_t* OG) {
;     ...
;     GlaSet s0, s1, s2;
;     GLA_LOAD(s0, 0); GLA_LOAD(s1, 1);
; #pragma unroll 1
;     for (int c = 0; c < 30; c += 3) {
;         GLA_LOAD(s2, c + 2); GLA_STEP(s0, c);
;         GLA_LOAD(s0, c + 3); GLA_STEP(s1, c + 1);
;         GLA_LOAD(s1, c + 4); GLA_STEP(s2, c + 2);
;     }
;     GLA_STEP(s0, 30); GLA_STEP(s1, 31);
;     ...
;     __syncthreads();
.Lgla_nost0:
	s_add_u32 s66, s66, 0x1000
	s_addc_u32 s67, s67, 0
	s_add_i32 s54, s54, 1
	s_waitcnt vmcnt(11)
	v_add_u32_e32 v5, s68, v0
	ds_read_b128 v[52:55], v5
	ds_read_b128 v[56:59], v5 offset:1024
	ds_read_b128 v[60:63], v5 offset:2048
	ds_read_b128 v[64:67], v5 offset:3072
	v_pk_mul_f32 v[8:9], v[8:9], v[36:37]
	v_pk_mul_f32 v[10:11], v[10:11], v[38:39]
	v_pk_mul_f32 v[12:13], v[12:13], v[36:37]
	v_pk_mul_f32 v[14:15], v[14:15], v[38:39]
	s_and_b32 s69, s54, 1
	s_mulk_i32 s69, 0x2200
	v_add_u32_e32 v6, s69, v3
	v_add_u32_e32 v7, s69, v4
	s_waitcnt lgkmcnt(0)
	s_nop 0
	v_mfma_f32_16x16x32_bf16 v[8:11], v[28:31], v[52:55], v[8:11]
	v_mfma_f32_16x16x32_bf16 v[12:15], v[28:31], v[60:63], v[12:15]
	v_mfma_f32_16x16x32_bf16 v[8:11], v[32:35], v[56:59], v[8:11]
	v_mfma_f32_16x16x32_bf16 v[12:15], v[32:35], v[64:67], v[12:15]
	global_load_dwordx4 v[16:19], v0, s[58:59]
	global_load_dwordx4 v[20:23], v0, s[58:59] offset:1024
	global_load_dwordx4 v[24:27], v1, s[60:61]
	s_add_u32 s58, s58, 0x4000
	s_addc_u32 s59, s59, 0
	s_add_u32 s60, s60, 0x200
	s_addc_u32 s61, s61, 0
	s_nop 7
	v_cvt_pk_bf16_f32 v104, v8, v9
	v_cvt_pk_bf16_f32 v105, v10, v11
	v_cvt_pk_bf16_f32 v106, v12, v13
	v_cvt_pk_bf16_f32 v107, v14, v15
	ds_write_b64 v6, v[104:105]
	ds_write_b64 v6, v[106:107] offset:4352
	s_waitcnt vmcnt(11)
	s_waitcnt lgkmcnt(0)
	s_barrier
	v_add_u32_e32 v5, s68, v108
	ds_read_b128 v[68:71], v7
	ds_read_b128 v[72:75], v7 offset:64
	ds_read_b128 v[76:79], v7 offset:128
	ds_read_b128 v[80:83], v7 offset:192
	ds_read_b128 v[84:87], v5
	ds_read_b128 v[88:91], v5 offset:1024
	ds_read_b128 v[92:95], v5 offset:2048
	ds_read_b128 v[96:99], v5 offset:3072
	s_add_i32 s0, s68, 0xffffb000
	s_cmp_lg_u32 s68, 0x5000
	s_cselect_b32 s0, s0, 0x14000
	s_mov_b64 exec, s[36:37]
	s_add_i32 m0, s0, s55
	s_nop 0
	global_load_lds_dwordx4 v109, s[62:63]
	s_mov_b64 exec, -1
	s_add_i32 m0, s0, s53
	s_nop 0
	global_load_lds_dwordx4 v0, s[64:65]
	global_load_lds_dwordx4 v0, s[64:65] offset:1024
	s_add_u32 s62, s62, 0x1000
	s_addc_u32 s63, s63, 0
	s_add_u32 s64, s64, 0x4000
	s_addc_u32 s65, s65, 0
	s_waitcnt lgkmcnt(0)
	v_mfma_f32_16x16x32_bf16 v[100:103], v[68:71], v[84:87], 0
	v_mfma_f32_16x16x32_bf16 v[100:103], v[72:75], v[88:91], v[100:103]
	v_mfma_f32_16x16x32_bf16 v[100:103], v[76:79], v[92:95], v[100:103]
	v_mfma_f32_16x16x32_bf16 v[100:103], v[80:83], v[96:99], v[100:103]
	s_add_i32 s68, s68, 0x5000
	s_cmp_lg_u32 s68, 0x19000
	s_cselect_b32 s68, s68, 0x5000
	s_nop 7
	v_pk_mul_f32 v[100:101], v[100:101], s[22:23] op_sel_hi:[1,0]
	v_pk_mul_f32 v[102:103], v[102:103], s[22:23] op_sel_hi:[1,0]
	s_cmpk_lt_u32 s54, 0x20
	v_cvt_pk_bf16_f32 v104, v100, v101
	v_cvt_pk_bf16_f32 v105, v102, v103
	s_cbranch_scc0 .Lgla_nost1
	global_store_dwordx2 v2, v[104:105], s[66:67]
.Lgla_nost1:
	s_add_u32 s66, s66, 0x1000
	s_addc_u32 s67, s67, 0
	s_add_i32 s54, s54, 1
	s_waitcnt vmcnt(11)
	v_add_u32_e32 v5, s68, v0
	ds_read_b128 v[52:55], v5
	ds_read_b128 v[56:59], v5 offset:1024
	ds_read_b128 v[60:63], v5 offset:2048
	ds_read_b128 v[64:67], v5 offset:3072
	v_pk_mul_f32 v[8:9], v[8:9], v[48:49]
	v_pk_mul_f32 v[10:11], v[10:11], v[50:51]
	v_pk_mul_f32 v[12:13], v[12:13], v[48:49]
	v_pk_mul_f32 v[14:15], v[14:15], v[50:51]
	s_and_b32 s69, s54, 1
	s_mulk_i32 s69, 0x2200
	v_add_u32_e32 v6, s69, v3
	v_add_u32_e32 v7, s69, v4
	s_waitcnt lgkmcnt(0)
	s_nop 0
	v_mfma_f32_16x16x32_bf16 v[8:11], v[40:43], v[52:55], v[8:11]
	v_mfma_f32_16x16x32_bf16 v[12:15], v[40:43], v[60:63], v[12:15]
	v_mfma_f32_16x16x32_bf16 v[8:11], v[44:47], v[56:59], v[8:11]
	v_mfma_f32_16x16x32_bf16 v[12:15], v[44:47], v[64:67], v[12:15]
	global_load_dwordx4 v[28:31], v0, s[58:59]
	global_load_dwordx4 v[32:35], v0, s[58:59] offset:1024
	global_load_dwordx4 v[36:39], v1, s[60:61]
	s_add_u32 s58, s58, 0x4000
	s_addc_u32 s59, s59, 0
	s_add_u32 s60, s60, 0x200
	s_addc_u32 s61, s61, 0
	s_nop 7
	v_cvt_pk_bf16_f32 v104, v8, v9
	v_cvt_pk_bf16_f32 v105, v10, v11
	v_cvt_pk_bf16_f32 v106, v12, v13
	v_cvt_pk_bf16_f32 v107, v14, v15
	ds_write_b64 v6, v[104:105]
	ds_write_b64 v6, v[106:107] offset:4352
	s_waitcnt vmcnt(11)
	s_waitcnt lgkmcnt(0)
	s_barrier
	v_add_u32_e32 v5, s68, v108
	ds_read_b128 v[68:71], v7
	ds_read_b128 v[72:75], v7 offset:64
	ds_read_b128 v[76:79], v7 offset:128
	ds_read_b128 v[80:83], v7 offset:192
	ds_read_b128 v[84:87], v5
	ds_read_b128 v[88:91], v5 offset:1024
	ds_read_b128 v[92:95], v5 offset:2048
	ds_read_b128 v[96:99], v5 offset:3072
	s_add_i32 s0, s68, 0xffffb000
	s_cmp_lg_u32 s68, 0x5000
	s_cselect_b32 s0, s0, 0x14000
	s_mov_b64 exec, s[36:37]
	s_add_i32 m0, s0, s55
	s_nop 0
	global_load_lds_dwordx4 v109, s[62:63]
	s_mov_b64 exec, -1
	s_add_i32 m0, s0, s53
	s_nop 0
	global_load_lds_dwordx4 v0, s[64:65]
	global_load_lds_dwordx4 v0, s[64:65] offset:1024
	s_add_u32 s62, s62, 0x1000
	s_addc_u32 s63, s63, 0
	s_add_u32 s64, s64, 0x4000
	s_addc_u32 s65, s65, 0
	s_waitcnt lgkmcnt(0)
	v_mfma_f32_16x16x32_bf16 v[100:103], v[68:71], v[84:87], 0
	v_mfma_f32_16x16x32_bf16 v[100:103], v[72:75], v[88:91], v[100:103]
	v_mfma_f32_16x16x32_bf16 v[100:103], v[76:79], v[92:95], v[100:103]
	v_mfma_f32_16x16x32_bf16 v[100:103], v[80:83], v[96:99], v[100:103]
	s_add_i32 s68, s68, 0x5000
	s_cmp_lg_u32 s68, 0x19000
	s_cselect_b32 s68, s68, 0x5000
	s_nop 7
	v_pk_mul_f32 v[100:101], v[100:101], s[22:23] op_sel_hi:[1,0]
	v_pk_mul_f32 v[102:103], v[102:103], s[22:23] op_sel_hi:[1,0]
	s_cmpk_lt_u32 s54, 0x20
	v_cvt_pk_bf16_f32 v104, v100, v101
	v_cvt_pk_bf16_f32 v105, v102, v103
	s_cbranch_scc0 .Lgla_nost2
	global_store_dwordx2 v2, v[104:105], s[66:67]
.Lgla_nost2:
	s_add_u32 s66, s66, 0x1000
	s_addc_u32 s67, s67, 0
	s_add_i32 s54, s54, 1
	s_cmpk_lt_u32 s54, 0x21
	s_cbranch_scc1 .Lgla_loop
	s_waitcnt vmcnt(0)
	s_waitcnt lgkmcnt(0)
	s_barrier
	s_add_i32 s52, s52, s15
	s_add_i32 s51, s51, s17
	s_cmpk_gt_i32 s52, 0xff
	s_cbranch_scc0 .LBB0_982
	s_branch .LBB0_980

; __global__ void __launch_bounds__(512, 2) mega_fwd(Args args) {
;     ...
;         {
;             const f32x4 gg = *(const f32x4*)(args.in[17] + lane * 4);
;             for (int m = gw; m < T; m += NGW) {
;                 u32x2 u[4], zu[4];
; #pragma unroll
;                 for (int h = 0; h < 4; ++h) {
;                     u[h] = *(const u32x2*)(OG + (size_t)(((m >> 11) * 4 + h) * 8 + (lane >> 3)) * (SEQ * 32) + (size_t)(m & 2047) * 32 + (lane & 7) * 4);
;                     zu[h] = *(const u32x2*)(Z + (size_t)m * ZLD + ZZR + h * 256 + lane * 4); }
.LBB0_1050:
	s_cmp_lt_i32 s92, 8
	s_cselect_b64 s[2:3], -1, 0
	s_and_b64 s[60:61], s[2:3], s[0:1]
	s_andn2_b64 vcc, exec, s[60:61]
	s_cbranch_vccnz .LBB0_1131
	s_cmpk_gt_i32 s82, 0x3fff
	s_cbranch_scc1 .LBB0_1054
	v_readlane_b32 s44, v238, 21
	v_lshlrev_b32_e32 v0, 4, v184
	v_readlane_b32 s46, v238, 23
	v_readlane_b32 s47, v238, 24
	s_ashr_i32 s83, s82, 31
	s_lshl_b64 s[0:1], s[82:83], 12
	s_add_u32 s12, s86, s0
	s_addc_u32 s13, s87, s1
	s_ashr_i32 s97, s96, 31
	global_load_dwordx4 v[0:3], v0, s[46:47]
	s_lshl_b64 s[24:25], s[96:97], 12
	s_mul_i32 s1, s82, 0x1800
	s_mul_hi_i32 s0, s82, 0x1800
	s_add_u32 s26, s86, s1
	s_waitcnt vmcnt(0)
	v_lshlrev_b32_e32 v4, 3, v185
	s_addc_u32 s27, s87, s0
	s_lshl_b32 s0, s80, 8
	s_lshl_b32 s1, s90, 5
	v_lshrrev_b32_e32 v14, 3, v184
	v_and_b32_e32 v4, 56, v4
	v_mov_b32_e32 v5, 0
	s_add_i32 s17, s0, s1
	s_mov_b32 s0, 0x358637bd
	v_lshl_add_u64 v[6:7], s[4:5], 0, v[4:5]
	v_or_b32_e32 v15, 8, v14
	v_or_b32_e32 v16, 16, v14
	v_or_b32_e32 v17, 24, v14
	v_lshlrev_b32_e32 v4, 3, v184
	s_mul_hi_i32 s14, s96, 0x1800
	s_mul_i32 s16, s96, 0x1800
	s_lshl_b32 s22, s15, 8
	s_mov_b32 s29, 0
	s_mov_b32 s23, 0xa800000
	s_mov_b32 s33, 0xa801000
	s_mov_b32 s36, 0x3b800000
	v_mov_b64_e32 v[8:9], s[0:1]
	s_mov_b32 s34, 0x800000
	s_mov_b32 s35, 0x6800000
	s_mov_b32 s37, s82
	v_readlane_b32 s45, v238, 22
	v_readlane_b32 s48, v238, 25
	v_readlane_b32 s49, v238, 26
	v_readlane_b32 s50, v238, 27
	v_readlane_b32 s51, v238, 28
	v_readlane_b32 s52, v238, 29
	v_readlane_b32 s53, v238, 30
	v_readlane_b32 s54, v238, 31
	v_readlane_b32 s55, v238, 32
	v_readlane_b32 s56, v238, 33
	v_readlane_b32 s57, v238, 34
	v_readlane_b32 s58, v238, 35
	v_readlane_b32 s59, v238, 36
	v_lshl_add_u64 v[110:111], s[26:27], 0, v[4:5]
	v_add_co_u32_e32 v118, vcc, s23, v110
	s_ashr_i32 s0, s37, 9
	s_nop 0
	v_addc_co_u32_e32 v119, vcc, 0, v111, vcc
	v_add_co_u32_e32 v120, vcc, s33, v110
	v_lshl_add_u64 v[112:113], s[12:13], 0, v[4:5]
	s_nop 0
	v_addc_co_u32_e32 v121, vcc, 0, v111, vcc
	s_and_b32 s1, s17, 0xffe0
	s_lshl_b32 s0, s0, 3
	v_add_co_u32_e32 v110, vcc, s35, v112
	s_lshl_b32 s28, s1, 1
	s_nop 0
	v_addc_co_u32_e32 v111, vcc, 0, v113, vcc
	global_load_dwordx2 v[88:89], v[118:119], off offset:3744
	s_nop 0
	global_load_dwordx2 v[90:91], v[120:121], off offset:160
	global_load_dwordx2 v[92:93], v[120:121], off offset:672
	s_nop 0
	global_load_dwordx2 v[94:95], v[120:121], off offset:1184
	s_and_b32 s1, s0, 0xffffffe0
	v_or_b32_e32 v126, s0, v17
	v_or_b32_e32 v128, s1, v14
	v_or_b32_e32 v130, s1, v15
	v_or_b32_e32 v132, s1, v16
	v_ashrrev_i32_e32 v127, 31, v126
	v_ashrrev_i32_e32 v129, 31, v128
	v_ashrrev_i32_e32 v131, 31, v130
	v_ashrrev_i32_e32 v133, 31, v132
	v_lshl_add_u64 v[124:125], v[6:7], 0, s[28:29]
	v_lshlrev_b64 v[126:127], 17, v[126:127]
	v_lshlrev_b64 v[128:129], 17, v[128:129]
	v_lshlrev_b64 v[130:131], 17, v[130:131]
	v_lshlrev_b64 v[132:133], 17, v[132:133]
	v_lshl_add_u64 v[126:127], v[124:125], 0, v[126:127]
	v_lshl_add_u64 v[128:129], v[124:125], 0, v[128:129]
	v_lshl_add_u64 v[130:131], v[124:125], 0, v[130:131]
	v_lshl_add_u64 v[124:125], v[124:125], 0, v[132:133]
	global_load_dwordx2 v[96:97], v[128:129], off
	s_nop 0
	global_load_dwordx2 v[98:99], v[130:131], off
	s_nop 0
	global_load_dwordx2 v[100:101], v[124:125], off
	s_nop 0
	global_load_dwordx2 v[102:103], v[126:127], off
	s_add_i32 s37, s37, s96
	s_add_u32 s12, s12, s24
	s_addc_u32 s13, s13, s25
	s_add_u32 s26, s26, s16
	s_addc_u32 s27, s27, s14
	s_add_i32 s17, s17, s22
	s_cmpk_gt_i32 s37, 0x3fff
	s_cselect_b32 s50, 1, 0
	s_waitcnt vmcnt(0)
.LBB0_1053:
	v_mov_b32_e32 v12, v88
	v_mov_b32_e32 v13, v89
	v_mov_b32_e32 v18, v90
	v_mov_b32_e32 v19, v91
	v_mov_b32_e32 v22, v92
	v_mov_b32_e32 v23, v93
	v_mov_b32_e32 v20, v94
	v_mov_b32_e32 v21, v95
	v_mov_b32_e32 v28, v96
	v_mov_b32_e32 v29, v97
	v_mov_b32_e32 v30, v98
	v_mov_b32_e32 v31, v99
	v_mov_b32_e32 v24, v100
	v_mov_b32_e32 v25, v101
	v_mov_b32_e32 v26, v102
	v_mov_b32_e32 v27, v103
	v_mov_b32_e32 v104, v110
	v_mov_b32_e32 v105, v111
	s_mov_b32 s51, 0
	s_cmp_lg_u32 s50, 0
	s_cbranch_scc1 .Lp7n_nopref
	v_lshl_add_u64 v[110:111], s[26:27], 0, v[4:5]
	v_add_co_u32_e32 v118, vcc, s23, v110
	s_ashr_i32 s0, s37, 9
	s_nop 0
	v_addc_co_u32_e32 v119, vcc, 0, v111, vcc
	v_add_co_u32_e32 v120, vcc, s33, v110
	v_lshl_add_u64 v[112:113], s[12:13], 0, v[4:5]
	s_nop 0
	v_addc_co_u32_e32 v121, vcc, 0, v111, vcc
	s_and_b32 s1, s17, 0xffe0
	s_lshl_b32 s0, s0, 3
	v_add_co_u32_e32 v110, vcc, s35, v112
	s_lshl_b32 s28, s1, 1
	s_nop 0
	v_addc_co_u32_e32 v111, vcc, 0, v113, vcc
	global_load_dwordx2 v[88:89], v[118:119], off offset:3744
	s_nop 0
	global_load_dwordx2 v[90:91], v[120:121], off offset:160
	global_load_dwordx2 v[92:93], v[120:121], off offset:672
	s_nop 0
	global_load_dwordx2 v[94:95], v[120:121], off offset:1184
	s_and_b32 s1, s0, 0xffffffe0
	v_or_b32_e32 v126, s0, v17
	v_or_b32_e32 v128, s1, v14
	v_or_b32_e32 v130, s1, v15
	v_or_b32_e32 v132, s1, v16
	v_ashrrev_i32_e32 v127, 31, v126
	v_ashrrev_i32_e32 v129, 31, v128
	v_ashrrev_i32_e32 v131, 31, v130
	v_ashrrev_i32_e32 v133, 31, v132
	v_lshl_add_u64 v[124:125], v[6:7], 0, s[28:29]
	v_lshlrev_b64 v[126:127], 17, v[126:127]
	v_lshlrev_b64 v[128:129], 17, v[128:129]
	v_lshlrev_b64 v[130:131], 17, v[130:131]
	v_lshlrev_b64 v[132:133], 17, v[132:133]
	v_lshl_add_u64 v[126:127], v[124:125], 0, v[126:127]
	v_lshl_add_u64 v[128:129], v[124:125], 0, v[128:129]
	v_lshl_add_u64 v[130:131], v[124:125], 0, v[130:131]
	v_lshl_add_u64 v[124:125], v[124:125], 0, v[132:133]
	global_load_dwordx2 v[96:97], v[128:129], off
	s_nop 0
	global_load_dwordx2 v[98:99], v[130:131], off
	s_nop 0
	global_load_dwordx2 v[100:101], v[124:125], off
	s_nop 0
	global_load_dwordx2 v[102:103], v[126:127], off
	s_add_i32 s37, s37, s96
	s_add_u32 s12, s12, s24
	s_addc_u32 s13, s13, s25
	s_add_u32 s26, s26, s16
	s_addc_u32 s27, s27, s14
	s_add_i32 s17, s17, s22
	s_cmpk_gt_i32 s37, 0x3fff
	s_cselect_b32 s50, 1, 0
	s_mov_b32 s51, 1
; __device__ __forceinline__ unsigned pk2(float lo, float hi) { f32x2_t v = {lo, hi}; bf16x2_t b = __builtin_convertvector(v, bf16x2_t); return __builtin_bit_cast(unsigned, b); }
; __device__ __forceinline__ float fast_silu(float g) { return g * __builtin_amdgcn_rcpf(1.f + __expf(-g)); }
; __global__ void __launch_bounds__(512, 2) mega_fwd(Args args) {
;     ...
;                 for (int h = 0; h < 4; ++h) {
;                     const float v0 = bflo(u[h].x), v1 = bfhi(u[h].x), v2 = bflo(u[h].y), v3 = bfhi(u[h].y);
;                     const float r = rsqrtf(wave_sum(v0 * v0 + v1 * v1 + v2 * v2 + v3 * v3) * (1.f / 256.f) + EPS);
;                     const float z0 = bflo(zu[h].x), z1 = bfhi(zu[h].x), z2 = bflo(zu[h].y), z3 = bfhi(zu[h].y);
;                     u32x2 w; w.x = pk2(v0 * r * gg.x * fast_silu(z0), v1 * r * gg.y * fast_silu(z1));
;                     w.y = pk2(v2 * r * gg.z * fast_silu(z2), v3 * r * gg.w * fast_silu(z3));
.Lp7n_nopref:
	v_lshlrev_b32_e32 v32, 16, v13
	v_and_b32_e32 v33, 0xffff0000, v13
	v_lshlrev_b32_e32 v34, 16, v12
	v_and_b32_e32 v35, 0xffff0000, v12
	v_lshlrev_b32_e32 v12, 16, v19
	v_and_b32_e32 v13, 0xffff0000, v19
	v_lshlrev_b32_e32 v36, 16, v18
	v_and_b32_e32 v37, 0xffff0000, v18
	v_lshlrev_b32_e32 v18, 16, v23
	v_and_b32_e32 v19, 0xffff0000, v23
	v_lshlrev_b32_e32 v38, 16, v22
	v_and_b32_e32 v39, 0xffff0000, v22
	v_lshlrev_b32_e32 v22, 16, v21
	v_and_b32_e32 v23, 0xffff0000, v21
	v_lshlrev_b32_e32 v40, 16, v20
	v_and_b32_e32 v41, 0xffff0000, v20
	v_mul_f32_e32 v20, 0xbfb8aa3b, v34
	v_mul_f32_e32 v21, 0xbfb8aa3b, v35
	v_mul_f32_e32 v42, 0xbfb8aa3b, v32
	v_mul_f32_e32 v43, 0xbfb8aa3b, v33
	v_mul_f32_e32 v44, 0xbfb8aa3b, v36
	v_mul_f32_e32 v45, 0xbfb8aa3b, v37
	v_mul_f32_e32 v46, 0xbfb8aa3b, v12
	v_mul_f32_e32 v47, 0xbfb8aa3b, v13
	v_mul_f32_e32 v48, 0xbfb8aa3b, v38
	v_mul_f32_e32 v49, 0xbfb8aa3b, v39
	v_mul_f32_e32 v52, 0xbfb8aa3b, v40
	v_mul_f32_e32 v53, 0xbfb8aa3b, v41
	v_exp_f32_e32 v56, v20
	v_exp_f32_e32 v57, v21
	v_exp_f32_e32 v58, v42
	v_exp_f32_e32 v59, v43
	v_mul_f32_e32 v50, 0xbfb8aa3b, v18
	v_mul_f32_e32 v51, 0xbfb8aa3b, v19
	v_mul_f32_e32 v54, 0xbfb8aa3b, v22
	v_mul_f32_e32 v55, 0xbfb8aa3b, v23
	v_exp_f32_e32 v60, v44
	v_exp_f32_e32 v61, v45
	v_exp_f32_e32 v62, v46
	v_exp_f32_e32 v63, v47
	v_exp_f32_e32 v64, v48
	v_exp_f32_e32 v65, v49
	v_exp_f32_e32 v68, v52
	v_exp_f32_e32 v69, v53
	v_exp_f32_e32 v66, v50
	v_exp_f32_e32 v67, v51
	v_exp_f32_e32 v70, v54
	v_exp_f32_e32 v71, v55
	v_lshlrev_b32_e32 v42, 16, v28
	v_and_b32_e32 v43, 0xffff0000, v28
	v_lshlrev_b32_e32 v44, 16, v30
	v_and_b32_e32 v45, 0xffff0000, v30
	v_lshlrev_b32_e32 v20, 16, v29
	v_and_b32_e32 v21, 0xffff0000, v29
	v_lshlrev_b32_e32 v28, 16, v31
	v_and_b32_e32 v29, 0xffff0000, v31
	v_lshlrev_b32_e32 v46, 16, v24
	v_and_b32_e32 v47, 0xffff0000, v24
	v_lshlrev_b32_e32 v48, 16, v26
	v_and_b32_e32 v49, 0xffff0000, v26
	v_pk_mul_f32 v[50:51], v[42:43], v[42:43]
	v_add_f32_e32 v72, 1.0, v56
	v_add_f32_e32 v73, 1.0, v57
	v_add_f32_e32 v74, 1.0, v58
	v_add_f32_e32 v75, 1.0, v59
	v_pk_mul_f32 v[54:55], v[44:45], v[44:45]
	v_lshlrev_b32_e32 v30, 16, v25
	v_and_b32_e32 v31, 0xffff0000, v25
	v_lshlrev_b32_e32 v24, 16, v27
	v_and_b32_e32 v25, 0xffff0000, v27
	v_pk_mul_f32 v[26:27], v[20:21], v[20:21]
	v_pk_mul_f32 v[52:53], v[28:29], v[28:29]
	v_add_f32_e32 v76, 1.0, v60
	v_add_f32_e32 v77, 1.0, v61
	v_add_f32_e32 v78, 1.0, v62
	v_add_f32_e32 v79, 1.0, v63
	v_pk_mul_f32 v[58:59], v[46:47], v[46:47]
	v_add_f32_e32 v80, 1.0, v64
	v_add_f32_e32 v81, 1.0, v65
	v_pk_mul_f32 v[62:63], v[48:49], v[48:49]
	v_add_f32_e32 v84, 1.0, v68
	v_add_f32_e32 v85, 1.0, v69
	v_rcp_f32_e32 v64, v72
	v_rcp_f32_e32 v65, v73
	v_add_f32_e32 v72, v50, v51
	v_rcp_f32_e32 v50, v74
	v_rcp_f32_e32 v51, v75
	v_add_f32_e32 v73, v54, v55
	v_pk_mul_f32 v[56:57], v[30:31], v[30:31]
	v_add_f32_e32 v82, 1.0, v66
	v_add_f32_e32 v83, 1.0, v67
	v_pk_mul_f32 v[60:61], v[24:25], v[24:25]
	v_add_f32_e32 v86, 1.0, v70
	v_add_f32_e32 v87, 1.0, v71
	v_rcp_f32_e32 v66, v76
	v_rcp_f32_e32 v67, v77
	v_rcp_f32_e32 v68, v80
	v_rcp_f32_e32 v69, v81
	v_add_f32_e32 v74, v58, v59
	v_rcp_f32_e32 v70, v84
	v_rcp_f32_e32 v71, v85
	v_add_f32_e32 v75, v62, v63
	v_add_f32_e32 v26, v26, v72
	v_add_f32_e32 v52, v52, v73
	v_add_f32_e32 v56, v56, v74
	v_add_f32_e32 v60, v60, v75
	v_add_f32_e32 v26, v27, v26
	v_add_f32_e32 v27, v53, v52
	v_add_f32_e32 v52, v57, v56
	v_add_f32_e32 v53, v61, v60
	v_add_f32_dpp v56, v26, v26 quad_perm:[1,0,3,2] row_mask:0xf bank_mask:0xf bound_ctrl:1
	v_add_f32_dpp v57, v27, v27 quad_perm:[1,0,3,2] row_mask:0xf bank_mask:0xf bound_ctrl:1
	v_add_f32_dpp v52, v52, v52 quad_perm:[1,0,3,2] row_mask:0xf bank_mask:0xf bound_ctrl:1
	v_add_f32_dpp v53, v53, v53 quad_perm:[1,0,3,2] row_mask:0xf bank_mask:0xf bound_ctrl:1
	v_add_f32_dpp v56, v56, v56 quad_perm:[2,3,0,1] row_mask:0xf bank_mask:0xf bound_ctrl:1
	v_pk_mul_f32 v[32:33], v[50:51], v[32:33]
	v_add_f32_dpp v50, v57, v57 quad_perm:[2,3,0,1] row_mask:0xf bank_mask:0xf bound_ctrl:1
	v_rcp_f32_e32 v54, v78
	v_rcp_f32_e32 v55, v79
	v_pk_mul_f32 v[26:27], v[64:65], v[34:35]
	v_pk_mul_f32 v[34:35], v[66:67], v[36:37]
	v_pk_mul_f32 v[36:37], v[68:69], v[38:39]
	v_add_f32_dpp v51, v52, v52 quad_perm:[2,3,0,1] row_mask:0xf bank_mask:0xf bound_ctrl:1
	v_pk_mul_f32 v[38:39], v[70:71], v[40:41]
	v_add_f32_dpp v40, v53, v53 quad_perm:[2,3,0,1] row_mask:0xf bank_mask:0xf bound_ctrl:1
	v_add_f32_dpp v41, v56, v56 row_half_mirror row_mask:0xf bank_mask:0xf bound_ctrl:1
	v_add_f32_dpp v50, v50, v50 row_half_mirror row_mask:0xf bank_mask:0xf bound_ctrl:1
	v_add_f32_dpp v51, v51, v51 row_half_mirror row_mask:0xf bank_mask:0xf bound_ctrl:1
	v_add_f32_dpp v40, v40, v40 row_half_mirror row_mask:0xf bank_mask:0xf bound_ctrl:1
	v_add_f32_dpp v41, v41, v41 row_mirror row_mask:0xf bank_mask:0xf bound_ctrl:1
	v_add_f32_dpp v50, v50, v50 row_mirror row_mask:0xf bank_mask:0xf bound_ctrl:1
	v_add_f32_dpp v51, v51, v51 row_mirror row_mask:0xf bank_mask:0xf bound_ctrl:1
	v_add_f32_dpp v40, v40, v40 row_mirror row_mask:0xf bank_mask:0xf bound_ctrl:1
	v_readlane_b32 s28, v41, 16
	v_readlane_b32 s42, v41, 48
	v_readlane_b32 s43, v50, 16
	v_readlane_b32 s44, v50, 48
	v_readlane_b32 s0, v41, 0
	v_readlane_b32 s1, v41, 32
	v_readlane_b32 s2, v50, 0
	v_readlane_b32 s3, v50, 32
	v_readlane_b32 s4, v51, 0
; __device__ __forceinline__ unsigned pk2(float lo, float hi) { f32x2_t v = {lo, hi}; bf16x2_t b = __builtin_convertvector(v, bf16x2_t); return __builtin_bit_cast(unsigned, b); }
; __device__ __forceinline__ float fast_silu(float g) { return g * __builtin_amdgcn_rcpf(1.f + __expf(-g)); }
; __global__ void __launch_bounds__(512, 2) mega_fwd(Args args) {
;     ...
;                     const float r = rsqrtf(wave_sum(v0 * v0 + v1 * v1 + v2 * v2 + v3 * v3) * (1.f / 256.f) + EPS);
;                     const float z0 = bflo(zu[h].x), z1 = bfhi(zu[h].x), z2 = bflo(zu[h].y), z3 = bfhi(zu[h].y);
;                     u32x2 w; w.x = pk2(v0 * r * gg.x * fast_silu(z0), v1 * r * gg.y * fast_silu(z1));
;                     w.y = pk2(v2 * r * gg.z * fast_silu(z2), v3 * r * gg.w * fast_silu(z3));
;                     *(u32x2*)(CAT + (size_t)m * 2048 + 1024 + h * 256 + lane * 4) = w;
;                 }
;             }
;     ...
;         __syncthreads();
;     ...
;         constexpr int QR = 128 * MLA_QF, NQB = SEQ / QR, NPAIR = NB * 8 * NQB / 2;
;     ...
; #pragma unroll 1
;         for (int rep = 0; rep < args.ph_lo + 1 + DUP_ATT; ++rep)
;         for (int p = cu; p < NPAIR; p += G) {
;             const int xcd_ = p & 7, idx_ = p >> 3, bh = (NPAIR % 8 == 0) ? xcd_ * (NPAIR / 8 / (NQB / 2)) + idx_ / (NQB / 2) : p / (NQB / 2), qp = (NPAIR % 8 == 0) ? idx_ % (NQB / 2) : p % (NQB / 2), b = bh >> 3, h = bh & 7;
; #pragma unroll 1
;             for (int half = 0; half < 2; ++half) {
;                 const int qb = half ? NQB - 1 - qp : qp;
;                 const size_t r0 = (size_t)b * SEQ + qb * QR;
;                 attn_unit_dma<192, MLA_QF>(lds, Qb + r0 * 1536 + h * 192, 1536, Kb + (size_t)b * SEQ * 1536 + h * 192, 1536, VT + (size_t)(h * 128) * T + (size_t)b * SEQ, T,
;                                CAT + r0 * 2048 + h * 128, 2048, (QR / 64) * (qb + 1), (qb * QR + 16 * MLA_QF * wave) / 64, nullptr, 1.f);
	v_readlane_b32 s45, v51, 16
	v_readlane_b32 s5, v51, 32
	v_readlane_b32 s46, v51, 48
	v_readlane_b32 s38, v40, 0
	v_readlane_b32 s47, v40, 16
	v_readlane_b32 s39, v40, 32
	v_readlane_b32 s48, v40, 48
	v_mov_b32_e32 v40, s28
	v_mov_b32_e32 v41, s42
	v_mov_b32_e32 v50, s43
	v_mov_b32_e32 v51, s44
	v_pk_mul_f32 v[12:13], v[54:55], v[12:13]
	v_mov_b32_e32 v52, s45
	v_mov_b32_e32 v53, s46
	v_mov_b32_e32 v54, s47
	v_mov_b32_e32 v55, s48
	v_pk_add_f32 v[40:41], s[0:1], v[40:41]
	v_pk_add_f32 v[50:51], s[2:3], v[50:51]
	v_pk_add_f32 v[52:53], s[4:5], v[52:53]
	v_pk_add_f32 v[54:55], s[38:39], v[54:55]
	v_mov_b32_e32 v56, v50
	v_mov_b32_e32 v57, v40
	v_mov_b32_e32 v40, v51
	v_mov_b32_e32 v50, v54
	v_mov_b32_e32 v51, v52
	v_mov_b32_e32 v52, v55
	v_pk_add_f32 v[40:41], v[56:57], v[40:41]
	v_pk_add_f32 v[50:51], v[50:51], v[52:53]
	v_pk_fma_f32 v[40:41], v[40:41], s[36:37], v[8:9] op_sel_hi:[1,0,0]
	v_pk_fma_f32 v[50:51], v[50:51], s[36:37], v[8:9] op_sel_hi:[1,0,0]
	v_mul_f32_e32 v52, 0x4b800000, v41
	v_cmp_gt_f32_e64 s[4:5], s34, v41
	v_mul_f32_e32 v53, 0x4b800000, v40
	v_cmp_gt_f32_e32 vcc, s34, v40
	v_mul_f32_e32 v54, 0x4b800000, v51
	v_mul_f32_e32 v55, 0x4b800000, v50
	v_cmp_gt_f32_e64 s[0:1], s34, v50
	v_cmp_gt_f32_e64 s[2:3], s34, v51
	v_cndmask_b32_e64 v41, v41, v52, s[4:5]
	v_cndmask_b32_e32 v40, v40, v53, vcc
	v_cndmask_b32_e64 v51, v51, v54, s[2:3]
	v_cndmask_b32_e64 v50, v50, v55, s[0:1]
	v_rsq_f32_e32 v41, v41
	v_rsq_f32_e32 v52, v40
	v_rsq_f32_e32 v51, v51
	v_rsq_f32_e32 v53, v50
	v_rcp_f32_e32 v58, v82
	v_rcp_f32_e32 v59, v83
	v_rcp_f32_e32 v62, v86
	v_rcp_f32_e32 v63, v87
	v_mul_f32_e32 v40, 0x45800000, v41
	v_mul_f32_e32 v50, 0x45800000, v52
	v_mul_f32_e32 v54, 0x45800000, v51
	v_mul_f32_e32 v55, 0x45800000, v53
	v_cndmask_b32_e64 v40, v41, v40, s[4:5]
	v_cndmask_b32_e32 v50, v52, v50, vcc
	v_cndmask_b32_e64 v52, v51, v54, s[2:3]
	v_cndmask_b32_e64 v54, v53, v55, s[0:1]
	v_pk_mul_f32 v[42:43], v[40:41], v[42:43] op_sel_hi:[0,1]
	v_pk_mul_f32 v[20:21], v[40:41], v[20:21] op_sel_hi:[0,1]
	v_pk_mul_f32 v[40:41], v[50:51], v[44:45] op_sel_hi:[0,1]
	v_pk_mul_f32 v[28:29], v[50:51], v[28:29] op_sel_hi:[0,1]
	v_pk_mul_f32 v[44:45], v[52:53], v[46:47] op_sel_hi:[0,1]
	v_pk_mul_f32 v[30:31], v[52:53], v[30:31] op_sel_hi:[0,1]
	v_pk_mul_f32 v[46:47], v[54:55], v[48:49] op_sel_hi:[0,1]
	v_pk_mul_f32 v[24:25], v[54:55], v[24:25] op_sel_hi:[0,1]
	v_pk_mul_f32 v[42:43], v[0:1], v[42:43]
	v_pk_mul_f32 v[20:21], v[2:3], v[20:21]
	v_pk_mul_f32 v[18:19], v[58:59], v[18:19]
	v_pk_mul_f32 v[22:23], v[62:63], v[22:23]
	v_pk_mul_f32 v[40:41], v[0:1], v[40:41]
	v_pk_mul_f32 v[28:29], v[2:3], v[28:29]
	v_pk_mul_f32 v[44:45], v[0:1], v[44:45]
	v_pk_mul_f32 v[30:31], v[2:3], v[30:31]
	v_pk_mul_f32 v[46:47], v[0:1], v[46:47]
	v_pk_mul_f32 v[24:25], v[2:3], v[24:25]
	v_pk_mul_f32 v[26:27], v[26:27], v[42:43]
	v_pk_mul_f32 v[20:21], v[32:33], v[20:21]
	v_pk_mul_f32 v[32:33], v[34:35], v[40:41]
	v_pk_mul_f32 v[12:13], v[12:13], v[28:29]
	v_pk_mul_f32 v[28:29], v[36:37], v[44:45]
	v_pk_mul_f32 v[18:19], v[18:19], v[30:31]
	v_pk_mul_f32 v[30:31], v[38:39], v[46:47]
	v_pk_mul_f32 v[22:23], v[22:23], v[24:25]
	v_cvt_pk_bf16_f32 v24, v26, v27
	v_cvt_pk_bf16_f32 v25, v20, v21
	v_cvt_pk_bf16_f32 v20, v32, v33
	v_cvt_pk_bf16_f32 v21, v12, v13
	v_cvt_pk_bf16_f32 v12, v28, v29
	v_cvt_pk_bf16_f32 v13, v18, v19
	v_cvt_pk_bf16_f32 v18, v30, v31
	v_cvt_pk_bf16_f32 v19, v22, v23
	global_store_dwordx2 v[104:105], v[24:25], off offset:2048
	global_store_dwordx2 v[104:105], v[20:21], off offset:2560
	global_store_dwordx2 v[104:105], v[12:13], off offset:3072
	global_store_dwordx2 v[104:105], v[18:19], off offset:3584
	s_cmp_lg_u32 s51, 0
	s_cbranch_scc0 .Lp7n_done
	s_waitcnt vmcnt(4)
	s_branch .LBB0_1053
.Lp7n_done:
.LBB0_1054:
	s_cmp_lt_i32 s92, 0
	s_mov_b32 s1, 0
	s_waitcnt vmcnt(0)
	s_barrier
	s_cbranch_scc1 .LBB0_1131
	v_lshrrev_b32_e32 v0, 1, v184
	v_and_b32_e32 v186, 24, v0
	v_or_b32_e32 v0, 0x600, v184
	s_movk_i32 s0, 0xa3e
	v_mul_u32_u24_sdwa v1, v0, s0 dst_sel:DWORD dst_unused:UNUSED_PAD src0_sel:WORD_0 src1_sel:DWORD
	v_mov_b32_e32 v2, 25
	v_mul_lo_u16_sdwa v2, v1, v2 dst_sel:DWORD dst_unused:UNUSED_PAD src0_sel:WORD_1 src1_sel:DWORD
	v_sub_u16_e32 v0, v0, v2
	s_cmpk_lt_i32 s80, 0x100
	s_movk_i32 s73, 0x600
	v_lshlrev_b16_e32 v2, 3, v0
	v_mov_b32_e32 v214, 0xb8
	v_cmp_ne_u16_e32 vcc, 24, v0
	v_writelane_b32 v238, s60, 21
	s_cselect_b64 s[2:3], -1, 0
	v_mov_b32_e32 v189, 0
	v_mul_u32_u24_sdwa v1, v1, s73 dst_sel:DWORD dst_unused:UNUSED_PAD src0_sel:WORD_1 src1_sel:DWORD
	v_cndmask_b32_e32 v0, v214, v2, vcc
	v_writelane_b32 v238, s61, 22
	v_and_b32_e32 v212, 15, v185
	v_mov_b32_e32 v187, v189
	v_and_b32_e32 v188, 48, v184
	v_or_b32_sdwa v215, v1, v0 dst_sel:DWORD dst_unused:UNUSED_PAD src0_sel:DWORD src1_sel:WORD_0
	v_cndmask_b32_e64 v0, 0, 1, s[2:3]
	v_writelane_b32 v238, s82, 38
	s_lshl_b32 s72, s90, 5
	v_lshl_add_u64 v[190:191], s[6:7], 0, v[188:189]
	v_or_b32_e32 v213, 0xfffff9c0, v184
	v_and_b32_e32 v216, 48, v185
	v_mul_u32_u24_e32 v217, 0x190, v212
	v_mul_u32_u24_e32 v218, 0x90, v212
	v_lshl_add_u64 v[192:193], s[40:41], 0, v[186:187]
	v_cmp_ne_u32_e64 s[2:3], 1, v0
	s_mov_b64 s[4:5], 0x80
	s_movk_i32 s74, 0xc00
	v_mov_b32_e32 v187, 0xc00
	s_mov_b32 s75, 0x38e38e39
	s_mov_b32 s76, 0x51eb851f
	v_mov_b32_e32 v219, 0xffff
	s_mov_b32 s77, 0
	v_writelane_b32 v238, s83, 39
	s_branch .LBB0_1057
